# cache-policy experiment: nt hint on the 32 H-tile stores of the two Up GEMM epilogues (streamed 275 MB each, read back only after the next barrier), on top of v15
# speedup vs baseline: 1.0104x; 1.0104x over previous
; DI unsigned pk2(float lo, float hi) { unsigned r; asm volatile("v_cvt_pk_bf16_f32 %0, %1, %2" : "=v"(r) : "v"(lo), "v"(hi)); return r; }
;     DI void operator()(const f32x4 (&acc)[2][2][4][2], const Unit& u, int wr, int wc, int fr, int fq, const Pre& pre) const {
;     ...
;             for (int m = 0; m < 4; ++m) { const int row = row0 + ai * 128 + m * 16; const float r = rs[ai][m];
; #pragma unroll
;                 for (int bj = 0; bj < 2; ++bj) { f32x4 v0 = acc[ai][bj][m][0] * r, v1 = acc[ai][bj][m][1] * r;
; #pragma unroll
;                     for (int e = 0; e < 4; ++e) { const float t0 = fmaxf(v0[e], 0.f), t1 = fmaxf(v1[e], 0.f); v0[e] = t0 * t0; v1[e] = t1 * t1; }
;                     u32x4v o; o.x = pk2(v0[0], v0[1]); o.y = pk2(v0[2], v0[3]); o.z = pk2(v1[0], v1[1]); o.w = pk2(v1[2], v1[3]);
;                     *(u32x4v*)(H + (size_t)row * 4096 + cb + bj * 128) = o; } }
.LBB0_1505:
	s_or_b64 exec, exec, s[4:5]
	v_pk_mul_f32 v[122:123], v[122:123], v[128:129] op_sel:[0,1]
	v_pk_mul_f32 v[126:127], v[126:127], v[128:129] op_sel:[0,1]
	v_pk_mul_f32 v[124:125], v[124:125], v[128:129] op_sel:[0,1]
	v_pk_mul_f32 v[120:121], v[120:121], v[128:129] op_sel:[0,1]
	v_max_f32_e32 v122, 0, v122
	v_lshl_or_b32 v130, s42, 8, v161
	v_max_f32_e32 v124, 0, v124
	v_max_f32_e32 v120, 0, v120
	v_max_f32_e32 v121, 0, v121
	v_max_f32_e32 v126, 0, v126
	v_mul_f32_e32 v134, v122, v122
	v_max_f32_e32 v122, 0, v127
	v_readlane_b32 s36, v255, 8
	v_ashrrev_i32_e32 v131, 31, v130
	v_lshlrev_b64 v[132:133], 13, v[190:191]
	v_mul_f32_e32 v124, v124, v124
	v_mul_f32_e32 v120, v120, v120
	v_max_f32_e32 v125, 0, v125
	v_mul_f32_e32 v121, v121, v121
	v_mul_f32_e32 v126, v126, v126
	v_max_f32_e32 v123, 0, v123
	v_mul_f32_e32 v127, v122, v122
	v_readlane_b32 s48, v255, 20
	v_readlane_b32 s49, v255, 21
	v_mul_f32_e32 v125, v125, v125
	v_mul_f32_e32 v135, v123, v123
	v_cvt_pk_bf16_f32 v122, v124, v125
	v_cvt_pk_bf16_f32 v123, v126, v127
	v_cvt_pk_bf16_f32 v124, v120, v121
	v_lshl_add_u64 v[126:127], s[48:49], 0, v[132:133]
	v_lshlrev_b64 v[120:121], 1, v[130:131]
	v_pk_mul_f32 v[114:115], v[114:115], v[128:129] op_sel:[0,1]
	v_pk_mul_f32 v[112:113], v[112:113], v[128:129] op_sel:[0,1]
	v_lshl_add_u64 v[126:127], v[126:127], 0, v[120:121]
	v_pk_mul_f32 v[118:119], v[118:119], v[128:129] op_sel:[0,1]
	v_pk_mul_f32 v[116:117], v[116:117], v[128:129] op_sel:[0,1]
	v_max_f32_e32 v112, 0, v112
	v_max_f32_e32 v113, 0, v113
	v_max_f32_e32 v114, 0, v114
	v_cvt_pk_bf16_f32 v125, v134, v135
	global_store_dwordx4 v[126:127], v[122:125], off nt
	v_max_f32_e32 v116, 0, v116
	v_max_f32_e32 v115, 0, v115
	v_mul_f32_e32 v122, v112, v112
	v_max_f32_e32 v112, 0, v117
	v_mul_f32_e32 v117, v113, v113
	v_max_f32_e32 v113, 0, v118
	v_mul_f32_e32 v118, v114, v114
	v_max_f32_e32 v114, 0, v119
	v_mul_f32_e32 v112, v112, v112
	v_mul_f32_e32 v113, v113, v113
	v_mul_f32_e32 v114, v114, v114
	v_pk_mul_f32 v[106:107], v[106:107], v[200:201] op_sel_hi:[1,0]
	v_pk_mul_f32 v[104:105], v[104:105], v[200:201] op_sel_hi:[1,0]
	v_mul_f32_e32 v116, v116, v116
	v_mul_f32_e32 v115, v115, v115
	v_cvt_pk_bf16_f32 v112, v116, v112
	v_cvt_pk_bf16_f32 v113, v113, v114
	v_cvt_pk_bf16_f32 v114, v122, v117
	v_pk_mul_f32 v[110:111], v[110:111], v[200:201] op_sel_hi:[1,0]
	v_pk_mul_f32 v[108:109], v[108:109], v[200:201] op_sel_hi:[1,0]
	v_max_f32_e32 v104, 0, v104
	v_max_f32_e32 v105, 0, v105
	v_max_f32_e32 v106, 0, v106
	v_cvt_pk_bf16_f32 v115, v118, v115
	global_store_dwordx4 v[126:127], v[112:115], off offset:256 nt
	v_max_f32_e32 v108, 0, v108
	v_mul_f32_e32 v108, v108, v108
	v_mul_f32_e32 v114, v104, v104
	v_max_f32_e32 v104, 0, v109
	v_mul_f32_e32 v109, v105, v105
	v_max_f32_e32 v105, 0, v110
	v_mul_f32_e32 v110, v106, v106
	v_max_f32_e32 v106, 0, v111
	v_lshlrev_b64 v[112:113], 13, v[198:199]
	v_mul_f32_e32 v104, v104, v104
	v_mul_f32_e32 v105, v105, v105
	v_mul_f32_e32 v106, v106, v106
	v_max_f32_e32 v107, 0, v107
	v_cvt_pk_bf16_f32 v104, v108, v104
	v_cvt_pk_bf16_f32 v105, v105, v106
	v_cvt_pk_bf16_f32 v106, v114, v109
	v_lshl_add_u64 v[108:109], s[48:49], 0, v[112:113]
	v_pk_mul_f32 v[98:99], v[98:99], v[200:201] op_sel_hi:[1,0]
	v_pk_mul_f32 v[96:97], v[96:97], v[200:201] op_sel_hi:[1,0]
	v_mul_f32_e32 v107, v107, v107
	v_lshl_add_u64 v[108:109], v[108:109], 0, v[120:121]
	v_pk_mul_f32 v[102:103], v[102:103], v[200:201] op_sel_hi:[1,0]
	v_pk_mul_f32 v[100:101], v[100:101], v[200:201] op_sel_hi:[1,0]
	v_max_f32_e32 v96, 0, v96
	v_max_f32_e32 v97, 0, v97
	v_max_f32_e32 v98, 0, v98
	v_cvt_pk_bf16_f32 v107, v110, v107
	global_store_dwordx4 v[108:109], v[104:107], off nt
	v_max_f32_e32 v100, 0, v100
	v_max_f32_e32 v99, 0, v99
	v_mul_f32_e32 v104, v96, v96
	v_max_f32_e32 v96, 0, v101
	v_mul_f32_e32 v101, v97, v97
	v_max_f32_e32 v97, 0, v102
	v_mul_f32_e32 v102, v98, v98
	v_max_f32_e32 v98, 0, v103
	v_mul_f32_e32 v96, v96, v96
	v_mul_f32_e32 v97, v97, v97
	v_mul_f32_e32 v98, v98, v98
	v_pk_mul_f32 v[90:91], v[90:91], v[200:201] op_sel:[0,1]
	v_pk_mul_f32 v[88:89], v[88:89], v[200:201] op_sel:[0,1]
	v_mul_f32_e32 v100, v100, v100
	v_mul_f32_e32 v99, v99, v99
	v_cvt_pk_bf16_f32 v96, v100, v96
	v_cvt_pk_bf16_f32 v97, v97, v98
	v_cvt_pk_bf16_f32 v98, v104, v101
	v_pk_mul_f32 v[94:95], v[94:95], v[200:201] op_sel:[0,1]
	v_pk_mul_f32 v[92:93], v[92:93], v[200:201] op_sel:[0,1]
	v_max_f32_e32 v88, 0, v88
	v_max_f32_e32 v89, 0, v89
	v_max_f32_e32 v90, 0, v90
	v_cvt_pk_bf16_f32 v99, v102, v99
	global_store_dwordx4 v[108:109], v[96:99], off offset:256 nt
	v_max_f32_e32 v92, 0, v92
	v_mul_f32_e32 v92, v92, v92
	v_mul_f32_e32 v98, v88, v88
	v_max_f32_e32 v88, 0, v93
	v_mul_f32_e32 v93, v89, v89
	v_max_f32_e32 v89, 0, v94
	v_mul_f32_e32 v94, v90, v90
	v_max_f32_e32 v90, 0, v95
	v_lshlrev_b64 v[96:97], 13, v[196:197]
	v_mul_f32_e32 v88, v88, v88
	v_mul_f32_e32 v89, v89, v89
	v_mul_f32_e32 v90, v90, v90
	v_max_f32_e32 v91, 0, v91
	v_cvt_pk_bf16_f32 v88, v92, v88
	v_cvt_pk_bf16_f32 v89, v89, v90
	v_cvt_pk_bf16_f32 v90, v98, v93
	v_lshl_add_u64 v[92:93], s[48:49], 0, v[96:97]
	v_pk_mul_f32 v[82:83], v[82:83], v[200:201] op_sel:[0,1]
	v_pk_mul_f32 v[80:81], v[80:81], v[200:201] op_sel:[0,1]
	v_mul_f32_e32 v91, v91, v91
	v_lshl_add_u64 v[92:93], v[92:93], 0, v[120:121]
	v_pk_mul_f32 v[86:87], v[86:87], v[200:201] op_sel:[0,1]
	v_pk_mul_f32 v[84:85], v[84:85], v[200:201] op_sel:[0,1]
	v_max_f32_e32 v80, 0, v80
	v_max_f32_e32 v81, 0, v81
	v_max_f32_e32 v82, 0, v82
	v_cvt_pk_bf16_f32 v91, v94, v91
	global_store_dwordx4 v[92:93], v[88:91], off nt
	v_max_f32_e32 v84, 0, v84
	v_max_f32_e32 v83, 0, v83
; DI unsigned pk2(float lo, float hi) { unsigned r; asm volatile("v_cvt_pk_bf16_f32 %0, %1, %2" : "=v"(r) : "v"(lo), "v"(hi)); return r; }
;     DI void operator()(const f32x4 (&acc)[2][2][4][2], const Unit& u, int wr, int wc, int fr, int fq, const Pre& pre) const {
;     ...
;             for (int m = 0; m < 4; ++m) { const int row = row0 + ai * 128 + m * 16; const float r = rs[ai][m];
; #pragma unroll
;                 for (int bj = 0; bj < 2; ++bj) { f32x4 v0 = acc[ai][bj][m][0] * r, v1 = acc[ai][bj][m][1] * r;
; #pragma unroll
;                     for (int e = 0; e < 4; ++e) { const float t0 = fmaxf(v0[e], 0.f), t1 = fmaxf(v1[e], 0.f); v0[e] = t0 * t0; v1[e] = t1 * t1; }
;                     u32x4v o; o.x = pk2(v0[0], v0[1]); o.y = pk2(v0[2], v0[3]); o.z = pk2(v1[0], v1[1]); o.w = pk2(v1[2], v1[3]);
;                     *(u32x4v*)(H + (size_t)row * 4096 + cb + bj * 128) = o; } }
	v_mul_f32_e32 v88, v80, v80
	v_max_f32_e32 v80, 0, v85
	v_mul_f32_e32 v85, v81, v81
	v_max_f32_e32 v81, 0, v86
	v_mul_f32_e32 v86, v82, v82
	v_max_f32_e32 v82, 0, v87
	v_mul_f32_e32 v80, v80, v80
	v_mul_f32_e32 v81, v81, v81
	v_mul_f32_e32 v82, v82, v82
	v_pk_mul_f32 v[74:75], v[74:75], v[144:145] op_sel_hi:[1,0]
	v_pk_mul_f32 v[72:73], v[72:73], v[144:145] op_sel_hi:[1,0]
	v_mul_f32_e32 v84, v84, v84
	v_mul_f32_e32 v83, v83, v83
	v_cvt_pk_bf16_f32 v80, v84, v80
	v_cvt_pk_bf16_f32 v81, v81, v82
	v_cvt_pk_bf16_f32 v82, v88, v85
	v_pk_mul_f32 v[78:79], v[78:79], v[144:145] op_sel_hi:[1,0]
	v_pk_mul_f32 v[76:77], v[76:77], v[144:145] op_sel_hi:[1,0]
	v_max_f32_e32 v72, 0, v72
	v_max_f32_e32 v73, 0, v73
	v_max_f32_e32 v74, 0, v74
	v_cvt_pk_bf16_f32 v83, v86, v83
	global_store_dwordx4 v[92:93], v[80:83], off offset:256 nt
	v_max_f32_e32 v76, 0, v76
	v_mul_f32_e32 v76, v76, v76
	v_mul_f32_e32 v82, v72, v72
	v_max_f32_e32 v72, 0, v77
	v_mul_f32_e32 v77, v73, v73
	v_max_f32_e32 v73, 0, v78
	v_mul_f32_e32 v78, v74, v74
	v_max_f32_e32 v74, 0, v79
	v_lshlrev_b64 v[80:81], 13, v[194:195]
	v_mul_f32_e32 v72, v72, v72
	v_mul_f32_e32 v73, v73, v73
	v_mul_f32_e32 v74, v74, v74
	v_max_f32_e32 v75, 0, v75
	v_cvt_pk_bf16_f32 v72, v76, v72
	v_cvt_pk_bf16_f32 v73, v73, v74
	v_cvt_pk_bf16_f32 v74, v82, v77
	v_lshl_add_u64 v[76:77], s[48:49], 0, v[80:81]
	v_pk_mul_f32 v[66:67], v[66:67], v[144:145] op_sel_hi:[1,0]
	v_pk_mul_f32 v[64:65], v[64:65], v[144:145] op_sel_hi:[1,0]
	v_mul_f32_e32 v75, v75, v75
	v_lshl_add_u64 v[76:77], v[76:77], 0, v[120:121]
	v_pk_mul_f32 v[70:71], v[70:71], v[144:145] op_sel_hi:[1,0]
	v_pk_mul_f32 v[68:69], v[68:69], v[144:145] op_sel_hi:[1,0]
	v_max_f32_e32 v64, 0, v64
	v_max_f32_e32 v65, 0, v65
	v_max_f32_e32 v66, 0, v66
	v_cvt_pk_bf16_f32 v75, v78, v75
	global_store_dwordx4 v[76:77], v[72:75], off nt
	v_max_f32_e32 v68, 0, v68
	v_max_f32_e32 v67, 0, v67
	v_mul_f32_e32 v72, v64, v64
	v_max_f32_e32 v64, 0, v69
	v_mul_f32_e32 v69, v65, v65
	v_max_f32_e32 v65, 0, v70
	v_mul_f32_e32 v70, v66, v66
	v_max_f32_e32 v66, 0, v71
	v_mul_f32_e32 v64, v64, v64
	v_mul_f32_e32 v65, v65, v65
	v_mul_f32_e32 v66, v66, v66
	v_pk_mul_f32 v[58:59], v[58:59], v[144:145] op_sel:[0,1]
	v_pk_mul_f32 v[56:57], v[56:57], v[144:145] op_sel:[0,1]
	v_mul_f32_e32 v68, v68, v68
	v_mul_f32_e32 v67, v67, v67
	v_cvt_pk_bf16_f32 v64, v68, v64
	v_cvt_pk_bf16_f32 v65, v65, v66
	v_cvt_pk_bf16_f32 v66, v72, v69
	v_pk_mul_f32 v[62:63], v[62:63], v[144:145] op_sel:[0,1]
	v_pk_mul_f32 v[60:61], v[60:61], v[144:145] op_sel:[0,1]
	v_max_f32_e32 v56, 0, v56
	v_max_f32_e32 v57, 0, v57
	v_max_f32_e32 v58, 0, v58
	v_cvt_pk_bf16_f32 v67, v70, v67
	global_store_dwordx4 v[76:77], v[64:67], off offset:256 nt
	v_max_f32_e32 v60, 0, v60
	v_mul_f32_e32 v60, v60, v60
	v_mul_f32_e32 v66, v56, v56
	v_max_f32_e32 v56, 0, v61
	v_mul_f32_e32 v61, v57, v57
	v_max_f32_e32 v57, 0, v62
	v_mul_f32_e32 v62, v58, v58
	v_max_f32_e32 v58, 0, v63
	v_lshlrev_b64 v[64:65], 13, v[192:193]
	v_mul_f32_e32 v56, v56, v56
	v_mul_f32_e32 v57, v57, v57
	v_mul_f32_e32 v58, v58, v58
	v_max_f32_e32 v59, 0, v59
	v_cvt_pk_bf16_f32 v56, v60, v56
	v_cvt_pk_bf16_f32 v57, v57, v58
	v_cvt_pk_bf16_f32 v58, v66, v61
	v_lshl_add_u64 v[60:61], s[48:49], 0, v[64:65]
	v_pk_mul_f32 v[48:49], v[48:49], v[144:145] op_sel:[0,1]
	v_mul_f32_e32 v59, v59, v59
	v_lshl_add_u64 v[60:61], v[60:61], 0, v[120:121]
	v_pk_mul_f32 v[52:53], v[52:53], v[144:145] op_sel:[0,1]
	v_pk_mul_f32 v[50:51], v[50:51], v[144:145] op_sel:[0,1]
	v_max_f32_e32 v48, 0, v48
	v_cvt_pk_bf16_f32 v59, v62, v59
	global_store_dwordx4 v[60:61], v[56:59], off nt
	v_pk_mul_f32 v[54:55], v[54:55], v[144:145] op_sel:[0,1]
	v_max_f32_e32 v49, 0, v49
	v_mul_f32_e32 v56, v48, v48
	v_max_f32_e32 v48, 0, v53
	v_max_f32_e32 v50, 0, v50
	v_max_f32_e32 v52, 0, v52
	v_mul_f32_e32 v48, v48, v48
	v_mul_f32_e32 v53, v49, v49
	v_max_f32_e32 v49, 0, v54
	v_mul_f32_e32 v54, v50, v50
	v_max_f32_e32 v50, 0, v55
	v_max_f32_e32 v51, 0, v51
	v_pk_mul_f32 v[42:43], v[42:43], v[136:137] op_sel_hi:[1,0]
	v_pk_mul_f32 v[40:41], v[40:41], v[136:137] op_sel_hi:[1,0]
	v_mul_f32_e32 v52, v52, v52
	v_mul_f32_e32 v49, v49, v49
	v_mul_f32_e32 v50, v50, v50
	v_mul_f32_e32 v51, v51, v51
	v_cvt_pk_bf16_f32 v48, v52, v48
	v_pk_mul_f32 v[46:47], v[46:47], v[136:137] op_sel_hi:[1,0]
	v_pk_mul_f32 v[44:45], v[44:45], v[136:137] op_sel_hi:[1,0]
	v_max_f32_e32 v40, 0, v40
	v_max_f32_e32 v41, 0, v41
	v_max_f32_e32 v42, 0, v42
	v_cvt_pk_bf16_f32 v49, v49, v50
	v_cvt_pk_bf16_f32 v50, v56, v53
	v_cvt_pk_bf16_f32 v51, v54, v51
	global_store_dwordx4 v[60:61], v[48:51], off offset:256 nt
	v_max_f32_e32 v44, 0, v44
	v_mul_f32_e32 v44, v44, v44
	v_mul_f32_e32 v48, v40, v40
	v_max_f32_e32 v40, 0, v45
	v_mul_f32_e32 v45, v41, v41
	v_max_f32_e32 v41, 0, v46
	v_mul_f32_e32 v46, v42, v42
	v_max_f32_e32 v42, 0, v47
	v_mul_f32_e32 v40, v40, v40
	v_mul_f32_e32 v41, v41, v41
	v_mul_f32_e32 v42, v42, v42
	v_ashrrev_i32_e32 v193, 31, v192
	v_cvt_pk_bf16_f32 v40, v44, v40
	v_cvt_pk_bf16_f32 v41, v41, v42
	v_cvt_pk_bf16_f32 v42, v48, v45
	v_lshlrev_b64 v[44:45], 13, v[192:193]
	v_max_f32_e32 v43, 0, v43
	v_lshl_add_u64 v[44:45], s[48:49], 0, v[44:45]
	v_mul_f32_e32 v43, v43, v43
	v_lshl_add_u64 v[44:45], v[44:45], 0, v[120:121]
	s_mov_b64 s[4:5], 0x20000
	v_cvt_pk_bf16_f32 v43, v46, v43
	v_lshl_add_u64 v[46:47], v[44:45], 0, s[4:5]
; DI unsigned pk2(float lo, float hi) { unsigned r; asm volatile("v_cvt_pk_bf16_f32 %0, %1, %2" : "=v"(r) : "v"(lo), "v"(hi)); return r; }
;     DI void operator()(const f32x4 (&acc)[2][2][4][2], const Unit& u, int wr, int wc, int fr, int fq, const Pre& pre) const {
;     ...
;             for (int m = 0; m < 4; ++m) { const int row = row0 + ai * 128 + m * 16; const float r = rs[ai][m];
; #pragma unroll
;                 for (int bj = 0; bj < 2; ++bj) { f32x4 v0 = acc[ai][bj][m][0] * r, v1 = acc[ai][bj][m][1] * r;
; #pragma unroll
;                     for (int e = 0; e < 4; ++e) { const float t0 = fmaxf(v0[e], 0.f), t1 = fmaxf(v1[e], 0.f); v0[e] = t0 * t0; v1[e] = t1 * t1; }
;                     u32x4v o; o.x = pk2(v0[0], v0[1]); o.y = pk2(v0[2], v0[3]); o.z = pk2(v1[0], v1[1]); o.w = pk2(v1[2], v1[3]);
;                     *(u32x4v*)(H + (size_t)row * 4096 + cb + bj * 128) = o; } }
	s_mov_b32 s4, 0x20000
	v_add_co_u32_e32 v48, vcc, s4, v44
	v_pk_mul_f32 v[32:33], v[32:33], v[136:137] op_sel_hi:[1,0]
	s_nop 0
	v_addc_co_u32_e32 v49, vcc, 0, v45, vcc
	v_pk_mul_f32 v[36:37], v[36:37], v[136:137] op_sel_hi:[1,0]
	v_pk_mul_f32 v[34:35], v[34:35], v[136:137] op_sel_hi:[1,0]
	v_max_f32_e32 v32, 0, v32
	global_store_dwordx4 v[48:49], v[40:43], off nt
	v_pk_mul_f32 v[38:39], v[38:39], v[136:137] op_sel_hi:[1,0]
	v_max_f32_e32 v33, 0, v33
	v_mul_f32_e32 v40, v32, v32
	v_max_f32_e32 v32, 0, v37
	v_max_f32_e32 v34, 0, v34
	v_max_f32_e32 v36, 0, v36
	v_mul_f32_e32 v32, v32, v32
	v_mul_f32_e32 v37, v33, v33
	v_max_f32_e32 v33, 0, v38
	v_mul_f32_e32 v38, v34, v34
	v_max_f32_e32 v34, 0, v39
	v_max_f32_e32 v35, 0, v35
	v_pk_mul_f32 v[26:27], v[26:27], v[136:137] op_sel:[0,1]
	v_pk_mul_f32 v[24:25], v[24:25], v[136:137] op_sel:[0,1]
	v_mul_f32_e32 v36, v36, v36
	v_mul_f32_e32 v33, v33, v33
	v_mul_f32_e32 v34, v34, v34
	v_mul_f32_e32 v35, v35, v35
	v_cvt_pk_bf16_f32 v32, v36, v32
	v_pk_mul_f32 v[30:31], v[30:31], v[136:137] op_sel:[0,1]
	v_pk_mul_f32 v[28:29], v[28:29], v[136:137] op_sel:[0,1]
	v_max_f32_e32 v24, 0, v24
	v_max_f32_e32 v25, 0, v25
	v_max_f32_e32 v26, 0, v26
	v_cvt_pk_bf16_f32 v33, v33, v34
	v_cvt_pk_bf16_f32 v34, v40, v37
	v_cvt_pk_bf16_f32 v35, v38, v35
	global_store_dwordx4 v[46:47], v[32:35], off offset:256 nt
	v_max_f32_e32 v28, 0, v28
	v_mul_f32_e32 v28, v28, v28
	v_mul_f32_e32 v32, v24, v24
	v_max_f32_e32 v24, 0, v29
	v_mul_f32_e32 v29, v25, v25
	v_max_f32_e32 v25, 0, v30
	v_mul_f32_e32 v30, v26, v26
	v_max_f32_e32 v26, 0, v31
	v_mul_f32_e32 v24, v24, v24
	v_mul_f32_e32 v25, v25, v25
	v_max_f32_e32 v27, 0, v27
	v_mul_f32_e32 v26, v26, v26
	s_mov_b64 s[4:5], 0x40000
	v_mul_f32_e32 v27, v27, v27
	v_cvt_pk_bf16_f32 v24, v28, v24
	v_cvt_pk_bf16_f32 v25, v25, v26
	v_cvt_pk_bf16_f32 v26, v32, v29
	v_lshl_add_u64 v[28:29], v[44:45], 0, s[4:5]
	s_mov_b32 s4, 0x40000
	v_cvt_pk_bf16_f32 v27, v30, v27
	v_add_co_u32_e32 v30, vcc, s4, v44
	v_pk_mul_f32 v[16:17], v[16:17], v[136:137] op_sel:[0,1]
	s_nop 0
	v_addc_co_u32_e32 v31, vcc, 0, v45, vcc
	v_pk_mul_f32 v[20:21], v[20:21], v[136:137] op_sel:[0,1]
	v_pk_mul_f32 v[18:19], v[18:19], v[136:137] op_sel:[0,1]
	v_max_f32_e32 v16, 0, v16
	global_store_dwordx4 v[30:31], v[24:27], off nt
	v_pk_mul_f32 v[22:23], v[22:23], v[136:137] op_sel:[0,1]
	v_max_f32_e32 v17, 0, v17
	v_mul_f32_e32 v24, v16, v16
	v_max_f32_e32 v16, 0, v21
	v_max_f32_e32 v18, 0, v18
	v_max_f32_e32 v20, 0, v20
	v_mul_f32_e32 v16, v16, v16
	v_mul_f32_e32 v21, v17, v17
	v_max_f32_e32 v17, 0, v22
	v_mul_f32_e32 v22, v18, v18
	v_max_f32_e32 v18, 0, v23
	v_max_f32_e32 v19, 0, v19
	v_pk_mul_f32 v[10:11], v[10:11], v[128:129] op_sel_hi:[1,0]
	v_pk_mul_f32 v[8:9], v[8:9], v[128:129] op_sel_hi:[1,0]
	v_mul_f32_e32 v20, v20, v20
	v_mul_f32_e32 v17, v17, v17
	v_mul_f32_e32 v18, v18, v18
	v_mul_f32_e32 v19, v19, v19
	v_cvt_pk_bf16_f32 v16, v20, v16
	v_pk_mul_f32 v[14:15], v[14:15], v[128:129] op_sel_hi:[1,0]
	v_pk_mul_f32 v[12:13], v[12:13], v[128:129] op_sel_hi:[1,0]
	v_max_f32_e32 v8, 0, v8
	v_max_f32_e32 v9, 0, v9
	v_max_f32_e32 v10, 0, v10
	v_cvt_pk_bf16_f32 v17, v17, v18
	v_cvt_pk_bf16_f32 v18, v24, v21
	v_cvt_pk_bf16_f32 v19, v22, v19
	global_store_dwordx4 v[28:29], v[16:19], off offset:256 nt
	v_max_f32_e32 v12, 0, v12
	v_mul_f32_e32 v12, v12, v12
	v_mul_f32_e32 v16, v8, v8
	v_max_f32_e32 v8, 0, v13
	v_mul_f32_e32 v13, v9, v9
	v_max_f32_e32 v9, 0, v14
	v_mul_f32_e32 v14, v10, v10
	v_max_f32_e32 v10, 0, v15
	v_mul_f32_e32 v8, v8, v8
	v_mul_f32_e32 v9, v9, v9
	v_max_f32_e32 v11, 0, v11
	v_mul_f32_e32 v10, v10, v10
	s_mov_b64 s[4:5], 0x60000
	v_mul_f32_e32 v11, v11, v11
	v_cvt_pk_bf16_f32 v8, v12, v8
	v_cvt_pk_bf16_f32 v9, v9, v10
	v_cvt_pk_bf16_f32 v10, v16, v13
	v_lshl_add_u64 v[12:13], v[44:45], 0, s[4:5]
	s_mov_b32 s4, 0x60000
	v_cvt_pk_bf16_f32 v11, v14, v11
	v_add_co_u32_e32 v14, vcc, s4, v44
	v_pk_mul_f32 v[2:3], v[2:3], v[128:129] op_sel_hi:[1,0]
	v_pk_mul_f32 v[0:1], v[0:1], v[128:129] op_sel_hi:[1,0]
	v_addc_co_u32_e32 v15, vcc, 0, v45, vcc
	v_pk_mul_f32 v[6:7], v[6:7], v[128:129] op_sel_hi:[1,0]
	v_pk_mul_f32 v[4:5], v[4:5], v[128:129] op_sel_hi:[1,0]
	v_max_f32_e32 v0, 0, v0
	v_max_f32_e32 v1, 0, v1
	v_max_f32_e32 v2, 0, v2
	v_readlane_b32 s38, v255, 10
	v_readlane_b32 s39, v255, 11
	v_readlane_b32 s40, v255, 12
	v_readlane_b32 s41, v255, 13
	v_readlane_b32 s42, v255, 14
	global_store_dwordx4 v[14:15], v[8:11], off nt
	v_max_f32_e32 v3, 0, v3
	v_max_f32_e32 v4, 0, v4
	v_mul_f32_e32 v8, v0, v0
	v_max_f32_e32 v0, 0, v5
	v_mul_f32_e32 v5, v1, v1
	v_max_f32_e32 v1, 0, v6
	v_mul_f32_e32 v6, v2, v2
	v_max_f32_e32 v2, 0, v7
	v_mul_f32_e32 v0, v0, v0
	v_mul_f32_e32 v1, v1, v1
	v_mul_f32_e32 v2, v2, v2
	v_mul_f32_e32 v3, v3, v3
	s_andn2_b64 vcc, exec, s[0:1]
	s_mov_b32 s42, s20
	s_mov_b32 s4, s22
	s_mov_b64 s[38:39], s[6:7]
	s_mov_b64 s[40:41], s[26:27]
	v_readlane_b32 s37, v255, 9
	v_readlane_b32 s43, v255, 15
	v_readlane_b32 s44, v255, 16
	v_readlane_b32 s45, v255, 17
	v_readlane_b32 s46, v255, 18
	v_readlane_b32 s47, v255, 19
	v_readlane_b32 s50, v255, 22
	v_readlane_b32 s51, v255, 23
	v_mul_f32_e32 v4, v4, v4
	v_cvt_pk_bf16_f32 v0, v4, v0
	v_cvt_pk_bf16_f32 v1, v1, v2
	v_cvt_pk_bf16_f32 v2, v8, v5
	v_cvt_pk_bf16_f32 v3, v6, v3
	global_store_dwordx4 v[12:13], v[0:3], off offset:256 nt
	s_cbranch_vccz .LBB0_1516

; DI unsigned pk2(float lo, float hi) { unsigned r; asm volatile("v_cvt_pk_bf16_f32 %0, %1, %2" : "=v"(r) : "v"(lo), "v"(hi)); return r; }
;     DI void operator()(const f32x4 (&acc)[2][2][4][2], const Unit& u, int wr, int wc, int fr, int fq, const Pre& pre) const {
;         const int cb = u.pn * 256 + wc * 32 + 8 * fq, row0 = u.pm * 256 + wr * 64 + fr;
;         float rs[2][4]; scales(pre, row0, fq, rs);
; #pragma unroll
;         for (int ai = 0; ai < 2; ++ai)
; #pragma unroll
;             for (int m = 0; m < 4; ++m) { const int row = row0 + ai * 128 + m * 16; const float r = rs[ai][m];
; #pragma unroll
;                 for (int bj = 0; bj < 2; ++bj) { f32x4 v0 = acc[ai][bj][m][0] * r, v1 = acc[ai][bj][m][1] * r;
; #pragma unroll
;                     for (int e = 0; e < 4; ++e) { const float t0 = fmaxf(v0[e], 0.f), t1 = fmaxf(v1[e], 0.f); v0[e] = t0 * t0; v1[e] = t1 * t1; }
;                     u32x4v o; o.x = pk2(v0[0], v0[1]); o.y = pk2(v0[2], v0[3]); o.z = pk2(v1[0], v1[1]); o.w = pk2(v1[2], v1[3]);
;                     *(u32x4v*)(H + (size_t)row * 4096 + cb + bj * 128) = o; } }
;     }
.LBB0_2443:
	s_or_b64 exec, exec, s[6:7]
	v_pk_mul_f32 v[122:123], v[122:123], v[164:165] op_sel:[0,1]
	v_pk_mul_f32 v[126:127], v[126:127], v[164:165] op_sel:[0,1]
	v_pk_mul_f32 v[124:125], v[124:125], v[164:165] op_sel:[0,1]
	v_pk_mul_f32 v[120:121], v[120:121], v[164:165] op_sel:[0,1]
	v_max_f32_e32 v122, 0, v122
	v_lshl_or_b32 v180, s51, 8, v157
	v_max_f32_e32 v124, 0, v124
	v_max_f32_e32 v120, 0, v120
	v_max_f32_e32 v121, 0, v121
	v_max_f32_e32 v126, 0, v126
	v_mul_f32_e32 v182, v122, v122
	v_max_f32_e32 v122, 0, v127
	v_readlane_b32 s44, v255, 8
	v_ashrrev_i32_e32 v181, 31, v180
	v_lshlrev_b64 v[160:161], 13, v[160:161]
	v_mul_f32_e32 v124, v124, v124
	v_mul_f32_e32 v120, v120, v120
	v_max_f32_e32 v125, 0, v125
	v_mul_f32_e32 v121, v121, v121
	v_mul_f32_e32 v126, v126, v126
	v_max_f32_e32 v123, 0, v123
	v_mul_f32_e32 v127, v122, v122
	v_readlane_b32 s56, v255, 20
	v_readlane_b32 s57, v255, 21
	v_mul_f32_e32 v125, v125, v125
	v_mul_f32_e32 v183, v123, v123
	v_cvt_pk_bf16_f32 v122, v124, v125
	v_cvt_pk_bf16_f32 v123, v126, v127
	v_cvt_pk_bf16_f32 v124, v120, v121
	v_lshl_add_u64 v[126:127], s[56:57], 0, v[160:161]
	v_lshlrev_b64 v[120:121], 1, v[180:181]
	v_pk_mul_f32 v[114:115], v[114:115], v[164:165] op_sel:[0,1]
	v_pk_mul_f32 v[112:113], v[112:113], v[164:165] op_sel:[0,1]
	v_lshl_add_u64 v[126:127], v[126:127], 0, v[120:121]
	v_pk_mul_f32 v[118:119], v[118:119], v[164:165] op_sel:[0,1]
	v_pk_mul_f32 v[116:117], v[116:117], v[164:165] op_sel:[0,1]
	v_max_f32_e32 v112, 0, v112
	v_max_f32_e32 v113, 0, v113
	v_max_f32_e32 v114, 0, v114
	v_cvt_pk_bf16_f32 v125, v182, v183
	global_store_dwordx4 v[126:127], v[122:125], off nt
	v_max_f32_e32 v116, 0, v116
	v_max_f32_e32 v115, 0, v115
	v_mul_f32_e32 v122, v112, v112
	v_max_f32_e32 v112, 0, v117
	v_mul_f32_e32 v117, v113, v113
	v_max_f32_e32 v113, 0, v118
	v_mul_f32_e32 v118, v114, v114
	v_max_f32_e32 v114, 0, v119
	v_mul_f32_e32 v112, v112, v112
	v_mul_f32_e32 v113, v113, v113
	v_mul_f32_e32 v114, v114, v114
	v_pk_mul_f32 v[106:107], v[106:107], v[176:177] op_sel_hi:[1,0]
	v_pk_mul_f32 v[104:105], v[104:105], v[176:177] op_sel_hi:[1,0]
	v_mul_f32_e32 v116, v116, v116
	v_mul_f32_e32 v115, v115, v115
	v_cvt_pk_bf16_f32 v112, v116, v112
	v_cvt_pk_bf16_f32 v113, v113, v114
	v_cvt_pk_bf16_f32 v114, v122, v117
	v_pk_mul_f32 v[110:111], v[110:111], v[176:177] op_sel_hi:[1,0]
	v_pk_mul_f32 v[108:109], v[108:109], v[176:177] op_sel_hi:[1,0]
	v_max_f32_e32 v104, 0, v104
	v_max_f32_e32 v105, 0, v105
	v_max_f32_e32 v106, 0, v106
	v_cvt_pk_bf16_f32 v115, v118, v115
	global_store_dwordx4 v[126:127], v[112:115], off offset:256 nt
	v_max_f32_e32 v108, 0, v108
	v_mul_f32_e32 v108, v108, v108
	v_mul_f32_e32 v114, v104, v104
	v_max_f32_e32 v104, 0, v109
	v_mul_f32_e32 v109, v105, v105
	v_max_f32_e32 v105, 0, v110
	v_mul_f32_e32 v110, v106, v106
	v_max_f32_e32 v106, 0, v111
	v_lshlrev_b64 v[112:113], 13, v[172:173]
	v_mul_f32_e32 v104, v104, v104
	v_mul_f32_e32 v105, v105, v105
	v_mul_f32_e32 v106, v106, v106
	v_max_f32_e32 v107, 0, v107
	v_cvt_pk_bf16_f32 v104, v108, v104
	v_cvt_pk_bf16_f32 v105, v105, v106
	v_cvt_pk_bf16_f32 v106, v114, v109
	v_lshl_add_u64 v[108:109], s[56:57], 0, v[112:113]
	v_pk_mul_f32 v[98:99], v[98:99], v[176:177] op_sel_hi:[1,0]
	v_pk_mul_f32 v[96:97], v[96:97], v[176:177] op_sel_hi:[1,0]
	v_mul_f32_e32 v107, v107, v107
	v_lshl_add_u64 v[108:109], v[108:109], 0, v[120:121]
	v_pk_mul_f32 v[102:103], v[102:103], v[176:177] op_sel_hi:[1,0]
	v_pk_mul_f32 v[100:101], v[100:101], v[176:177] op_sel_hi:[1,0]
	v_max_f32_e32 v96, 0, v96
	v_max_f32_e32 v97, 0, v97
	v_max_f32_e32 v98, 0, v98
	v_cvt_pk_bf16_f32 v107, v110, v107
	global_store_dwordx4 v[108:109], v[104:107], off nt
	v_max_f32_e32 v100, 0, v100
	v_max_f32_e32 v99, 0, v99
	v_mul_f32_e32 v104, v96, v96
	v_max_f32_e32 v96, 0, v101
	v_mul_f32_e32 v101, v97, v97
	v_max_f32_e32 v97, 0, v102
	v_mul_f32_e32 v102, v98, v98
	v_max_f32_e32 v98, 0, v103
	v_mul_f32_e32 v96, v96, v96
	v_mul_f32_e32 v97, v97, v97
	v_mul_f32_e32 v98, v98, v98
	v_pk_mul_f32 v[90:91], v[90:91], v[176:177] op_sel:[0,1]
	v_pk_mul_f32 v[88:89], v[88:89], v[176:177] op_sel:[0,1]
	v_mul_f32_e32 v100, v100, v100
	v_mul_f32_e32 v99, v99, v99
	v_cvt_pk_bf16_f32 v96, v100, v96
	v_cvt_pk_bf16_f32 v97, v97, v98
	v_cvt_pk_bf16_f32 v98, v104, v101
	v_pk_mul_f32 v[94:95], v[94:95], v[176:177] op_sel:[0,1]
	v_pk_mul_f32 v[92:93], v[92:93], v[176:177] op_sel:[0,1]
	v_max_f32_e32 v88, 0, v88
	v_max_f32_e32 v89, 0, v89
	v_max_f32_e32 v90, 0, v90
	v_cvt_pk_bf16_f32 v99, v102, v99
	global_store_dwordx4 v[108:109], v[96:99], off offset:256 nt
	v_max_f32_e32 v92, 0, v92
	v_mul_f32_e32 v92, v92, v92
	v_mul_f32_e32 v98, v88, v88
	v_max_f32_e32 v88, 0, v93
	v_mul_f32_e32 v93, v89, v89
	v_max_f32_e32 v89, 0, v94
	v_mul_f32_e32 v94, v90, v90
	v_max_f32_e32 v90, 0, v95
	v_lshlrev_b64 v[96:97], 13, v[170:171]
	v_mul_f32_e32 v88, v88, v88
	v_mul_f32_e32 v89, v89, v89
	v_mul_f32_e32 v90, v90, v90
	v_max_f32_e32 v91, 0, v91
	v_cvt_pk_bf16_f32 v88, v92, v88
	v_cvt_pk_bf16_f32 v89, v89, v90
	v_cvt_pk_bf16_f32 v90, v98, v93
	v_lshl_add_u64 v[92:93], s[56:57], 0, v[96:97]
	v_pk_mul_f32 v[82:83], v[82:83], v[176:177] op_sel:[0,1]
	v_pk_mul_f32 v[80:81], v[80:81], v[176:177] op_sel:[0,1]
	v_mul_f32_e32 v91, v91, v91
	v_lshl_add_u64 v[92:93], v[92:93], 0, v[120:121]
	v_pk_mul_f32 v[86:87], v[86:87], v[176:177] op_sel:[0,1]
	v_pk_mul_f32 v[84:85], v[84:85], v[176:177] op_sel:[0,1]
	v_max_f32_e32 v80, 0, v80
	v_max_f32_e32 v81, 0, v81
	v_max_f32_e32 v82, 0, v82
	v_cvt_pk_bf16_f32 v91, v94, v91
	global_store_dwordx4 v[92:93], v[88:91], off nt
	v_max_f32_e32 v84, 0, v84
	v_max_f32_e32 v83, 0, v83
; DI unsigned pk2(float lo, float hi) { unsigned r; asm volatile("v_cvt_pk_bf16_f32 %0, %1, %2" : "=v"(r) : "v"(lo), "v"(hi)); return r; }
;     DI void operator()(const f32x4 (&acc)[2][2][4][2], const Unit& u, int wr, int wc, int fr, int fq, const Pre& pre) const {
;         const int cb = u.pn * 256 + wc * 32 + 8 * fq, row0 = u.pm * 256 + wr * 64 + fr;
;         float rs[2][4]; scales(pre, row0, fq, rs);
; #pragma unroll
;         for (int ai = 0; ai < 2; ++ai)
; #pragma unroll
;             for (int m = 0; m < 4; ++m) { const int row = row0 + ai * 128 + m * 16; const float r = rs[ai][m];
; #pragma unroll
;                 for (int bj = 0; bj < 2; ++bj) { f32x4 v0 = acc[ai][bj][m][0] * r, v1 = acc[ai][bj][m][1] * r;
; #pragma unroll
;                     for (int e = 0; e < 4; ++e) { const float t0 = fmaxf(v0[e], 0.f), t1 = fmaxf(v1[e], 0.f); v0[e] = t0 * t0; v1[e] = t1 * t1; }
;                     u32x4v o; o.x = pk2(v0[0], v0[1]); o.y = pk2(v0[2], v0[3]); o.z = pk2(v1[0], v1[1]); o.w = pk2(v1[2], v1[3]);
;                     *(u32x4v*)(H + (size_t)row * 4096 + cb + bj * 128) = o; } }
;     }
	v_mul_f32_e32 v88, v80, v80
	v_max_f32_e32 v80, 0, v85
	v_mul_f32_e32 v85, v81, v81
	v_max_f32_e32 v81, 0, v86
	v_mul_f32_e32 v86, v82, v82
	v_max_f32_e32 v82, 0, v87
	v_mul_f32_e32 v80, v80, v80
	v_mul_f32_e32 v81, v81, v81
	v_mul_f32_e32 v82, v82, v82
	v_pk_mul_f32 v[74:75], v[74:75], v[174:175] op_sel_hi:[1,0]
	v_pk_mul_f32 v[72:73], v[72:73], v[174:175] op_sel_hi:[1,0]
	v_mul_f32_e32 v84, v84, v84
	v_mul_f32_e32 v83, v83, v83
	v_cvt_pk_bf16_f32 v80, v84, v80
	v_cvt_pk_bf16_f32 v81, v81, v82
	v_cvt_pk_bf16_f32 v82, v88, v85
	v_pk_mul_f32 v[78:79], v[78:79], v[174:175] op_sel_hi:[1,0]
	v_pk_mul_f32 v[76:77], v[76:77], v[174:175] op_sel_hi:[1,0]
	v_max_f32_e32 v72, 0, v72
	v_max_f32_e32 v73, 0, v73
	v_max_f32_e32 v74, 0, v74
	v_cvt_pk_bf16_f32 v83, v86, v83
	global_store_dwordx4 v[92:93], v[80:83], off offset:256 nt
	v_max_f32_e32 v76, 0, v76
	v_mul_f32_e32 v76, v76, v76
	v_mul_f32_e32 v82, v72, v72
	v_max_f32_e32 v72, 0, v77
	v_mul_f32_e32 v77, v73, v73
	v_max_f32_e32 v73, 0, v78
	v_mul_f32_e32 v78, v74, v74
	v_max_f32_e32 v74, 0, v79
	v_lshlrev_b64 v[80:81], 13, v[166:167]
	v_mul_f32_e32 v72, v72, v72
	v_mul_f32_e32 v73, v73, v73
	v_mul_f32_e32 v74, v74, v74
	v_max_f32_e32 v75, 0, v75
	v_cvt_pk_bf16_f32 v72, v76, v72
	v_cvt_pk_bf16_f32 v73, v73, v74
	v_cvt_pk_bf16_f32 v74, v82, v77
	v_lshl_add_u64 v[76:77], s[56:57], 0, v[80:81]
	v_pk_mul_f32 v[66:67], v[66:67], v[174:175] op_sel_hi:[1,0]
	v_pk_mul_f32 v[64:65], v[64:65], v[174:175] op_sel_hi:[1,0]
	v_mul_f32_e32 v75, v75, v75
	v_lshl_add_u64 v[76:77], v[76:77], 0, v[120:121]
	v_pk_mul_f32 v[70:71], v[70:71], v[174:175] op_sel_hi:[1,0]
	v_pk_mul_f32 v[68:69], v[68:69], v[174:175] op_sel_hi:[1,0]
	v_max_f32_e32 v64, 0, v64
	v_max_f32_e32 v65, 0, v65
	v_max_f32_e32 v66, 0, v66
	v_cvt_pk_bf16_f32 v75, v78, v75
	global_store_dwordx4 v[76:77], v[72:75], off nt
	v_max_f32_e32 v68, 0, v68
	v_max_f32_e32 v67, 0, v67
	v_mul_f32_e32 v72, v64, v64
	v_max_f32_e32 v64, 0, v69
	v_mul_f32_e32 v69, v65, v65
	v_max_f32_e32 v65, 0, v70
	v_mul_f32_e32 v70, v66, v66
	v_max_f32_e32 v66, 0, v71
	v_mul_f32_e32 v64, v64, v64
	v_mul_f32_e32 v65, v65, v65
	v_mul_f32_e32 v66, v66, v66
	v_pk_mul_f32 v[58:59], v[58:59], v[174:175] op_sel:[0,1]
	v_pk_mul_f32 v[56:57], v[56:57], v[174:175] op_sel:[0,1]
	v_mul_f32_e32 v68, v68, v68
	v_mul_f32_e32 v67, v67, v67
	v_cvt_pk_bf16_f32 v64, v68, v64
	v_cvt_pk_bf16_f32 v65, v65, v66
	v_cvt_pk_bf16_f32 v66, v72, v69
	v_pk_mul_f32 v[62:63], v[62:63], v[174:175] op_sel:[0,1]
	v_pk_mul_f32 v[60:61], v[60:61], v[174:175] op_sel:[0,1]
	v_max_f32_e32 v56, 0, v56
	v_max_f32_e32 v57, 0, v57
	v_max_f32_e32 v58, 0, v58
	v_cvt_pk_bf16_f32 v67, v70, v67
	global_store_dwordx4 v[76:77], v[64:67], off offset:256 nt
	v_max_f32_e32 v60, 0, v60
	v_mul_f32_e32 v60, v60, v60
	v_mul_f32_e32 v66, v56, v56
	v_max_f32_e32 v56, 0, v61
	v_mul_f32_e32 v61, v57, v57
	v_max_f32_e32 v57, 0, v62
	v_mul_f32_e32 v62, v58, v58
	v_max_f32_e32 v58, 0, v63
	v_lshlrev_b64 v[64:65], 13, v[162:163]
	v_mul_f32_e32 v56, v56, v56
	v_mul_f32_e32 v57, v57, v57
	v_mul_f32_e32 v58, v58, v58
	v_max_f32_e32 v59, 0, v59
	v_cvt_pk_bf16_f32 v56, v60, v56
	v_cvt_pk_bf16_f32 v57, v57, v58
	v_cvt_pk_bf16_f32 v58, v66, v61
	v_lshl_add_u64 v[60:61], s[56:57], 0, v[64:65]
	v_pk_mul_f32 v[48:49], v[48:49], v[174:175] op_sel:[0,1]
	v_mul_f32_e32 v59, v59, v59
	v_lshl_add_u64 v[60:61], v[60:61], 0, v[120:121]
	v_pk_mul_f32 v[52:53], v[52:53], v[174:175] op_sel:[0,1]
	v_pk_mul_f32 v[50:51], v[50:51], v[174:175] op_sel:[0,1]
	v_max_f32_e32 v48, 0, v48
	v_cvt_pk_bf16_f32 v59, v62, v59
	global_store_dwordx4 v[60:61], v[56:59], off nt
	v_pk_mul_f32 v[54:55], v[54:55], v[174:175] op_sel:[0,1]
	v_max_f32_e32 v49, 0, v49
	v_mul_f32_e32 v56, v48, v48
	v_max_f32_e32 v48, 0, v53
	v_max_f32_e32 v50, 0, v50
	v_max_f32_e32 v52, 0, v52
	v_mul_f32_e32 v48, v48, v48
	v_mul_f32_e32 v53, v49, v49
	v_max_f32_e32 v49, 0, v54
	v_mul_f32_e32 v54, v50, v50
	v_max_f32_e32 v50, 0, v55
	v_max_f32_e32 v51, 0, v51
	v_pk_mul_f32 v[42:43], v[42:43], v[168:169] op_sel_hi:[1,0]
	v_pk_mul_f32 v[40:41], v[40:41], v[168:169] op_sel_hi:[1,0]
	v_mul_f32_e32 v52, v52, v52
	v_mul_f32_e32 v49, v49, v49
	v_mul_f32_e32 v50, v50, v50
	v_mul_f32_e32 v51, v51, v51
	v_cvt_pk_bf16_f32 v48, v52, v48
	v_pk_mul_f32 v[46:47], v[46:47], v[168:169] op_sel_hi:[1,0]
	v_pk_mul_f32 v[44:45], v[44:45], v[168:169] op_sel_hi:[1,0]
	v_max_f32_e32 v40, 0, v40
	v_max_f32_e32 v41, 0, v41
	v_max_f32_e32 v42, 0, v42
	v_cvt_pk_bf16_f32 v49, v49, v50
	v_cvt_pk_bf16_f32 v50, v56, v53
	v_cvt_pk_bf16_f32 v51, v54, v51
	global_store_dwordx4 v[60:61], v[48:51], off offset:256 nt
	v_max_f32_e32 v44, 0, v44
	v_mul_f32_e32 v44, v44, v44
	v_mul_f32_e32 v48, v40, v40
	v_max_f32_e32 v40, 0, v45
	v_mul_f32_e32 v45, v41, v41
	v_max_f32_e32 v41, 0, v46
	v_mul_f32_e32 v46, v42, v42
	v_max_f32_e32 v42, 0, v47
	v_mul_f32_e32 v40, v40, v40
	v_mul_f32_e32 v41, v41, v41
	v_mul_f32_e32 v42, v42, v42
	v_ashrrev_i32_e32 v163, 31, v162
	v_cvt_pk_bf16_f32 v40, v44, v40
	v_cvt_pk_bf16_f32 v41, v41, v42
	v_cvt_pk_bf16_f32 v42, v48, v45
	v_lshlrev_b64 v[44:45], 13, v[162:163]
	v_lshl_add_u64 v[44:45], s[56:57], 0, v[44:45]
	v_lshl_add_u64 v[44:45], v[44:45], 0, v[120:121]
	v_max_f32_e32 v43, 0, v43
	v_add_co_u32_e32 v48, vcc, s71, v44
; DI unsigned pk2(float lo, float hi) { unsigned r; asm volatile("v_cvt_pk_bf16_f32 %0, %1, %2" : "=v"(r) : "v"(lo), "v"(hi)); return r; }
; template <class Epi, class Sched>
; __device__ __forceinline__ void gemm_phase(PG8_LAS unsigned char* lds, const Gemm g, const Sched& S, const Epi& E) {
;     ...
;         if (!has_next) break;
;     DI void operator()(const f32x4 (&acc)[2][2][4][2], const Unit& u, int wr, int wc, int fr, int fq, const Pre& pre) const {
;         const int cb = u.pn * 256 + wc * 32 + 8 * fq, row0 = u.pm * 256 + wr * 64 + fr;
;         float rs[2][4]; scales(pre, row0, fq, rs);
; #pragma unroll
;         for (int ai = 0; ai < 2; ++ai)
; #pragma unroll
;             for (int m = 0; m < 4; ++m) { const int row = row0 + ai * 128 + m * 16; const float r = rs[ai][m];
; #pragma unroll
;                 for (int bj = 0; bj < 2; ++bj) { f32x4 v0 = acc[ai][bj][m][0] * r, v1 = acc[ai][bj][m][1] * r;
; #pragma unroll
;                     for (int e = 0; e < 4; ++e) { const float t0 = fmaxf(v0[e], 0.f), t1 = fmaxf(v1[e], 0.f); v0[e] = t0 * t0; v1[e] = t1 * t1; }
;                     u32x4v o; o.x = pk2(v0[0], v0[1]); o.y = pk2(v0[2], v0[3]); o.z = pk2(v1[0], v1[1]); o.w = pk2(v1[2], v1[3]);
;                     *(u32x4v*)(H + (size_t)row * 4096 + cb + bj * 128) = o; } }
;     }
	v_pk_mul_f32 v[32:33], v[32:33], v[168:169] op_sel_hi:[1,0]
	v_mul_f32_e32 v43, v43, v43
	v_addc_co_u32_e32 v49, vcc, 0, v45, vcc
	v_pk_mul_f32 v[36:37], v[36:37], v[168:169] op_sel_hi:[1,0]
	v_pk_mul_f32 v[34:35], v[34:35], v[168:169] op_sel_hi:[1,0]
	v_max_f32_e32 v32, 0, v32
	v_cvt_pk_bf16_f32 v43, v46, v43
	global_store_dwordx4 v[48:49], v[40:43], off nt
	v_pk_mul_f32 v[38:39], v[38:39], v[168:169] op_sel_hi:[1,0]
	v_max_f32_e32 v33, 0, v33
	v_mul_f32_e32 v40, v32, v32
	v_max_f32_e32 v32, 0, v37
	v_max_f32_e32 v34, 0, v34
	v_max_f32_e32 v36, 0, v36
	v_mul_f32_e32 v32, v32, v32
	v_mul_f32_e32 v37, v33, v33
	v_max_f32_e32 v33, 0, v38
	v_mul_f32_e32 v38, v34, v34
	v_max_f32_e32 v34, 0, v39
	v_max_f32_e32 v35, 0, v35
	v_pk_mul_f32 v[26:27], v[26:27], v[168:169] op_sel:[0,1]
	v_pk_mul_f32 v[24:25], v[24:25], v[168:169] op_sel:[0,1]
	v_lshl_add_u64 v[46:47], v[44:45], 0, s[22:23]
	v_mul_f32_e32 v36, v36, v36
	v_mul_f32_e32 v33, v33, v33
	v_mul_f32_e32 v34, v34, v34
	v_mul_f32_e32 v35, v35, v35
	v_cvt_pk_bf16_f32 v32, v36, v32
	v_pk_mul_f32 v[30:31], v[30:31], v[168:169] op_sel:[0,1]
	v_pk_mul_f32 v[28:29], v[28:29], v[168:169] op_sel:[0,1]
	v_max_f32_e32 v24, 0, v24
	v_max_f32_e32 v25, 0, v25
	v_max_f32_e32 v26, 0, v26
	v_cvt_pk_bf16_f32 v33, v33, v34
	v_cvt_pk_bf16_f32 v34, v40, v37
	v_cvt_pk_bf16_f32 v35, v38, v35
	global_store_dwordx4 v[46:47], v[32:35], off offset:256 nt
	v_max_f32_e32 v27, 0, v27
	v_max_f32_e32 v28, 0, v28
	v_mul_f32_e32 v32, v24, v24
	v_max_f32_e32 v24, 0, v29
	v_mul_f32_e32 v29, v25, v25
	v_max_f32_e32 v25, 0, v30
	v_mul_f32_e32 v30, v26, v26
	v_max_f32_e32 v26, 0, v31
	v_mul_f32_e32 v24, v24, v24
	v_mul_f32_e32 v25, v25, v25
	v_mul_f32_e32 v26, v26, v26
	v_mul_f32_e32 v27, v27, v27
	v_mul_f32_e32 v28, v28, v28
	v_cvt_pk_bf16_f32 v24, v28, v24
	v_cvt_pk_bf16_f32 v25, v25, v26
	v_cvt_pk_bf16_f32 v26, v32, v29
	v_cvt_pk_bf16_f32 v27, v30, v27
	v_add_co_u32_e32 v30, vcc, s72, v44
	v_pk_mul_f32 v[16:17], v[16:17], v[168:169] op_sel:[0,1]
	s_nop 0
	v_addc_co_u32_e32 v31, vcc, 0, v45, vcc
	v_pk_mul_f32 v[20:21], v[20:21], v[168:169] op_sel:[0,1]
	v_pk_mul_f32 v[18:19], v[18:19], v[168:169] op_sel:[0,1]
	v_max_f32_e32 v16, 0, v16
	global_store_dwordx4 v[30:31], v[24:27], off nt
	v_pk_mul_f32 v[22:23], v[22:23], v[168:169] op_sel:[0,1]
	v_max_f32_e32 v17, 0, v17
	v_mul_f32_e32 v24, v16, v16
	v_max_f32_e32 v16, 0, v21
	v_max_f32_e32 v18, 0, v18
	v_max_f32_e32 v20, 0, v20
	v_mul_f32_e32 v16, v16, v16
	v_mul_f32_e32 v21, v17, v17
	v_max_f32_e32 v17, 0, v22
	v_mul_f32_e32 v22, v18, v18
	v_max_f32_e32 v18, 0, v23
	v_max_f32_e32 v19, 0, v19
	v_pk_mul_f32 v[10:11], v[10:11], v[164:165] op_sel_hi:[1,0]
	v_pk_mul_f32 v[8:9], v[8:9], v[164:165] op_sel_hi:[1,0]
	v_lshl_add_u64 v[28:29], v[44:45], 0, s[10:11]
	v_mul_f32_e32 v20, v20, v20
	v_mul_f32_e32 v17, v17, v17
	v_mul_f32_e32 v18, v18, v18
	v_mul_f32_e32 v19, v19, v19
	v_cvt_pk_bf16_f32 v16, v20, v16
	v_pk_mul_f32 v[14:15], v[14:15], v[164:165] op_sel_hi:[1,0]
	v_pk_mul_f32 v[12:13], v[12:13], v[164:165] op_sel_hi:[1,0]
	v_max_f32_e32 v8, 0, v8
	v_max_f32_e32 v9, 0, v9
	v_max_f32_e32 v10, 0, v10
	v_cvt_pk_bf16_f32 v17, v17, v18
	v_cvt_pk_bf16_f32 v18, v24, v21
	v_cvt_pk_bf16_f32 v19, v22, v19
	global_store_dwordx4 v[28:29], v[16:19], off offset:256 nt
	v_max_f32_e32 v11, 0, v11
	v_max_f32_e32 v12, 0, v12
	v_mul_f32_e32 v16, v8, v8
	v_max_f32_e32 v8, 0, v13
	v_mul_f32_e32 v13, v9, v9
	v_max_f32_e32 v9, 0, v14
	v_mul_f32_e32 v14, v10, v10
	v_max_f32_e32 v10, 0, v15
	v_mul_f32_e32 v8, v8, v8
	v_mul_f32_e32 v9, v9, v9
	v_mul_f32_e32 v10, v10, v10
	v_mul_f32_e32 v11, v11, v11
	v_mul_f32_e32 v12, v12, v12
	v_cvt_pk_bf16_f32 v8, v12, v8
	v_cvt_pk_bf16_f32 v9, v9, v10
	v_cvt_pk_bf16_f32 v10, v16, v13
	v_cvt_pk_bf16_f32 v11, v14, v11
	v_add_co_u32_e32 v14, vcc, s73, v44
	v_pk_mul_f32 v[2:3], v[2:3], v[164:165] op_sel_hi:[1,0]
	v_pk_mul_f32 v[0:1], v[0:1], v[164:165] op_sel_hi:[1,0]
	v_addc_co_u32_e32 v15, vcc, 0, v45, vcc
	v_pk_mul_f32 v[6:7], v[6:7], v[164:165] op_sel_hi:[1,0]
	v_pk_mul_f32 v[4:5], v[4:5], v[164:165] op_sel_hi:[1,0]
	v_max_f32_e32 v0, 0, v0
	v_max_f32_e32 v1, 0, v1
	v_max_f32_e32 v2, 0, v2
	v_readlane_b32 s51, v255, 15
	global_store_dwordx4 v[14:15], v[8:11], off nt
	v_max_f32_e32 v3, 0, v3
	v_lshl_add_u64 v[12:13], v[44:45], 0, s[24:25]
	v_mul_f32_e32 v8, v0, v0
	v_max_f32_e32 v0, 0, v5
	v_mul_f32_e32 v5, v1, v1
	v_max_f32_e32 v1, 0, v6
	v_mul_f32_e32 v6, v2, v2
	v_max_f32_e32 v2, 0, v7
	v_max_f32_e32 v4, 0, v4
	v_mul_f32_e32 v0, v0, v0
	v_mul_f32_e32 v1, v1, v1
	v_mul_f32_e32 v2, v2, v2
	v_mul_f32_e32 v3, v3, v3
	s_andn2_b64 vcc, exec, s[0:1]
	s_mov_b32 s51, s26
	s_mov_b32 s6, s36
	s_mov_b64 s[8:9], s[40:41]
	s_mov_b64 s[12:13], s[38:39]
	v_readlane_b32 s45, v255, 9
	v_readlane_b32 s46, v255, 10
	v_readlane_b32 s47, v255, 11
	v_readlane_b32 s48, v255, 12
	v_readlane_b32 s49, v255, 13
	v_readlane_b32 s50, v255, 14
	v_readlane_b32 s52, v255, 16
	v_readlane_b32 s53, v255, 17
	v_readlane_b32 s54, v255, 18
	v_readlane_b32 s55, v255, 19
	v_readlane_b32 s58, v255, 22
	v_readlane_b32 s59, v255, 23
	v_mul_f32_e32 v4, v4, v4
	v_cvt_pk_bf16_f32 v0, v4, v0
	v_cvt_pk_bf16_f32 v1, v1, v2
	v_cvt_pk_bf16_f32 v2, v8, v5
	v_cvt_pk_bf16_f32 v3, v6, v3
	global_store_dwordx4 v[12:13], v[0:3], off offset:256 nt
	s_cbranch_vccz .LBB0_2454
